# team stagger: teams 4-7 start P1 ~4us late (s_sleep) so the teams' HBM bursts miss each other; P3 mid-K hook aligned across the two wave halves
# speedup vs baseline: 1.0059x; 1.0059x over previous
.LBB0_165:
	s_or_b64 exec, exec, s[0:1]
	s_lshr_b32 s97, s75, 2
	s_mul_i32 s97, s97, 4
.Lstag_loop:
	s_cmp_eq_u32 s97, 0
	s_cbranch_scc1 .Lstag_done
	s_sleep 37
	s_sub_u32 s97, s97, 1
	s_branch .Lstag_loop
.Lstag_done:
	s_add_u32 s48, s70, 0x200000
	s_addc_u32 s49, s71, 0
	v_readlane_b32 s0, v245, 2
	s_cmp_gt_i32 s0, 15
	s_waitcnt lgkmcnt(0)
	s_barrier
	s_cbranch_scc1 .LBB0_167
	v_mov_b32_e32 v2, v0
	s_lshl_b32 s0, s75, 1
	v_mbcnt_lo_u32_b32 v104, -1, 0
	v_mbcnt_hi_u32_b32 v104, -1, v104
	s_add_i32 s0, s0, s80
	v_readfirstlane_b32 s4, v2
	s_and_b32 s1, s4, 0xffffffc0
	v_add_u32_e32 v20, s1, v104
	s_ashr_i32 s1, s0, 31
	v_lshlrev_b32_e32 v42, 2, v20
	s_lshl_b64 s[2:3], s[0:1], 16
	v_ashrrev_i32_e32 v43, 31, v42
	s_add_u32 s2, s18, s2
	s_addc_u32 s3, s19, s3
	v_lshlrev_b64 v[2:3], 5, v[42:43]
	v_lshl_add_u64 v[18:19], s[2:3], 0, v[2:3]
	global_load_dwordx4 v[2:5], v[18:19], off
	global_load_dwordx4 v[6:9], v[18:19], off offset:32
	global_load_dwordx4 v[10:13], v[18:19], off offset:64
	global_load_dwordx4 v[14:17], v[18:19], off offset:96
	global_load_dwordx4 v[68:71], v[18:19], off offset:16
	global_load_dwordx4 v[72:75], v[18:19], off offset:48
	global_load_dwordx4 v[76:79], v[18:19], off offset:80
	global_load_dwordx4 v[80:83], v[18:19], off offset:112
	s_lshr_b32 s1, s4, 3
	v_lshl_add_u32 v105, v20, 6, 0
	s_and_b32 s1, s1, 0x1ffffff8
	s_add_i32 s1, s1, 0
	v_lshl_add_u32 v106, v104, 9, s1
	v_mbcnt_hi_u32_b32 v107, -1, v1
	v_and_b32_e32 v108, 64, v107
	s_waitcnt vmcnt(8)
	v_add_u32_e32 v100, -1, v107
	v_cmp_lt_i32_e32 vcc, v100, v108
	v_add_u32_e32 v102, -2, v107
	s_lshl_b32 s0, s0, 3
	v_cndmask_b32_e32 v100, v100, v107, vcc
	v_lshlrev_b32_e32 v101, 2, v100
	v_cmp_gt_i32_e32 vcc, 1, v104
	s_ashr_i32 s1, s0, 31
	s_mov_b32 s2, 0x652b82fe
	s_lshl_b64 s[4:5], s[0:1], 13
	s_mov_b32 s3, 0xbff71547
	s_add_u32 s4, s48, s4
	s_addc_u32 s5, s49, s5
	s_waitcnt vmcnt(7)
	v_cvt_f64_f32_e32 v[66:67], v2
	v_cvt_f64_f32_e32 v[58:59], v3
	v_cvt_f64_f32_e32 v[50:51], v4
	v_cvt_f64_f32_e32 v[40:41], v5
	s_waitcnt vmcnt(6)
	v_cvt_f64_f32_e32 v[64:65], v6
	s_waitcnt vmcnt(4)
	v_cvt_f64_f32_e32 v[60:61], v14
	v_cvt_f64_f32_e32 v[56:57], v7
	v_cvt_f64_f32_e32 v[52:53], v15
	v_cvt_f64_f32_e32 v[48:49], v8
	v_cvt_f64_f32_e32 v[44:45], v16
	v_cvt_f64_f32_e32 v[38:39], v9
	v_cvt_f64_f32_e32 v[34:35], v17
	s_waitcnt vmcnt(3)
	v_cvt_f64_f32_e32 v[32:33], v68
	s_waitcnt vmcnt(2)
	v_cvt_f64_f32_e32 v[30:31], v72
	v_cvt_f64_f32_e32 v[24:25], v69
	v_cvt_f64_f32_e32 v[22:23], v73
	v_cvt_f64_f32_e32 v[16:17], v70
	v_cvt_f64_f32_e32 v[14:15], v74
	v_cvt_f64_f32_e32 v[8:9], v71
	v_cvt_f64_f32_e32 v[6:7], v75
	v_add_f64 v[68:69], v[66:67], 0
	v_add_f64 v[70:71], v[58:59], 0
	v_add_f64 v[72:73], v[50:51], 0
	v_add_f64 v[74:75], v[40:41], 0
	v_cvt_f64_f32_e32 v[62:63], v10
	v_cvt_f64_f32_e32 v[54:55], v11
	v_cvt_f64_f32_e32 v[46:47], v12
	v_cvt_f64_f32_e32 v[36:37], v13
	s_waitcnt vmcnt(1)
	v_cvt_f64_f32_e32 v[28:29], v76
	s_waitcnt vmcnt(0)
	v_cvt_f64_f32_e32 v[26:27], v80
	v_cvt_f64_f32_e32 v[20:21], v77
	v_cvt_f64_f32_e32 v[18:19], v81
	v_cvt_f64_f32_e32 v[12:13], v78
	v_cvt_f64_f32_e32 v[10:11], v82
	v_cvt_f64_f32_e32 v[4:5], v79
	v_cvt_f64_f32_e32 v[2:3], v83
	v_add_f64 v[76:77], v[32:33], 0
	v_add_f64 v[78:79], v[24:25], 0
	v_add_f64 v[80:81], v[16:17], 0
	v_add_f64 v[82:83], v[8:9], 0
	v_add_f64 v[68:69], v[68:69], v[64:65]
	v_add_f64 v[70:71], v[70:71], v[56:57]
	v_add_f64 v[72:73], v[72:73], v[48:49]
	v_add_f64 v[74:75], v[74:75], v[38:39]
	v_add_f64 v[76:77], v[76:77], v[30:31]
	v_add_f64 v[78:79], v[78:79], v[22:23]
	v_add_f64 v[80:81], v[80:81], v[14:15]
	v_add_f64 v[82:83], v[82:83], v[6:7]
	v_add_f64 v[68:69], v[68:69], v[62:63]
	v_add_f64 v[70:71], v[70:71], v[54:55]
	v_add_f64 v[72:73], v[72:73], v[46:47]
	v_add_f64 v[74:75], v[74:75], v[36:37]
	v_add_f64 v[76:77], v[76:77], v[28:29]
	v_add_f64 v[78:79], v[78:79], v[20:21]
	v_add_f64 v[80:81], v[80:81], v[12:13]
	v_add_f64 v[82:83], v[82:83], v[4:5]
	v_add_f64 v[68:69], v[68:69], v[60:61]
	v_add_f64 v[70:71], v[70:71], v[52:53]
	v_add_f64 v[72:73], v[72:73], v[44:45]
	v_add_f64 v[74:75], v[74:75], v[34:35]
	v_add_f64 v[76:77], v[76:77], v[26:27]
	v_add_f64 v[78:79], v[78:79], v[18:19]
	v_add_f64 v[80:81], v[80:81], v[10:11]
	v_add_f64 v[82:83], v[82:83], v[2:3]
	ds_write_b128 v105, v[68:71]
	ds_write_b128 v105, v[72:75] offset:16
	ds_write_b128 v105, v[76:79] offset:32
	ds_write_b128 v105, v[80:83] offset:48
	s_waitcnt lgkmcnt(0)
	s_barrier
	ds_read2_b64 v[68:71], v106 offset1:8
	ds_read2_b64 v[72:75], v106 offset0:16 offset1:24
	ds_read2_b64 v[76:79], v106 offset0:32 offset1:40
	ds_read2_b64 v[80:83], v106 offset0:48 offset1:56
	s_waitcnt lgkmcnt(3)
	v_add_f64 v[84:85], v[68:69], 0
	v_add_f64 v[86:87], v[84:85], v[70:71]
	s_waitcnt lgkmcnt(2)
	v_add_f64 v[88:89], v[86:87], v[72:73]
	v_add_f64 v[90:91], v[88:89], v[74:75]
	s_waitcnt lgkmcnt(1)
	v_add_f64 v[92:93], v[90:91], v[76:77]
	v_add_f64 v[94:95], v[92:93], v[78:79]
	s_waitcnt lgkmcnt(0)
	v_add_f64 v[96:97], v[94:95], v[80:81]
	v_add_f64 v[98:99], v[96:97], v[82:83]
	ds_bpermute_b32 v100, v101, v98
	ds_bpermute_b32 v101, v101, v99
	s_waitcnt lgkmcnt(0)
	v_add_f64 v[100:101], v[98:99], v[100:101]
	v_cndmask_b32_e32 v101, v101, v99, vcc
	v_cndmask_b32_e32 v100, v100, v98, vcc
	v_cmp_lt_i32_e32 vcc, v102, v108
	s_nop 1
	v_cndmask_b32_e32 v102, v102, v107, vcc
	v_lshlrev_b32_e32 v103, 2, v102
	ds_bpermute_b32 v102, v103, v100
	ds_bpermute_b32 v103, v103, v101
	v_cmp_gt_i32_e32 vcc, 2, v104
	s_waitcnt lgkmcnt(0)
	v_add_f64 v[102:103], v[100:101], v[102:103]
	v_cndmask_b32_e32 v100, v102, v100, vcc
	v_add_u32_e32 v102, -4, v107
	v_cndmask_b32_e32 v101, v103, v101, vcc
	v_cmp_lt_i32_e32 vcc, v102, v108
	s_nop 1
	v_cndmask_b32_e32 v102, v102, v107, vcc
	v_lshlrev_b32_e32 v103, 2, v102
	ds_bpermute_b32 v102, v103, v100
	ds_bpermute_b32 v103, v103, v101
	v_cmp_gt_i32_e32 vcc, 4, v104
	s_waitcnt lgkmcnt(0)
	v_add_f64 v[102:103], v[100:101], v[102:103]
	v_cndmask_b32_e32 v100, v102, v100, vcc
	v_add_u32_e32 v102, -8, v107
	v_cndmask_b32_e32 v101, v103, v101, vcc
	v_cmp_lt_i32_e32 vcc, v102, v108
	s_nop 1
	v_cndmask_b32_e32 v102, v102, v107, vcc
	v_lshlrev_b32_e32 v103, 2, v102
	ds_bpermute_b32 v102, v103, v100
	ds_bpermute_b32 v103, v103, v101
	v_cmp_gt_i32_e32 vcc, 8, v104
	s_waitcnt lgkmcnt(0)
	v_add_f64 v[102:103], v[100:101], v[102:103]
	v_cndmask_b32_e32 v100, v102, v100, vcc
	v_add_u32_e32 v102, -16, v107
	v_cndmask_b32_e32 v101, v103, v101, vcc
	v_cmp_lt_i32_e32 vcc, v102, v108
	s_nop 1
	v_cndmask_b32_e32 v102, v102, v107, vcc
	v_lshlrev_b32_e32 v103, 2, v102
	ds_bpermute_b32 v102, v103, v100
	ds_bpermute_b32 v103, v103, v101
	v_cmp_gt_i32_e32 vcc, 16, v104
	s_waitcnt lgkmcnt(0)
	v_add_f64 v[102:103], v[100:101], v[102:103]
	v_cndmask_b32_e32 v100, v102, v100, vcc
	v_subrev_u32_e32 v102, 32, v107
	v_cndmask_b32_e32 v101, v103, v101, vcc
	v_cmp_lt_i32_e32 vcc, v102, v108
	s_nop 1
	v_cndmask_b32_e32 v102, v102, v107, vcc
	v_lshlrev_b32_e32 v103, 2, v102
	ds_bpermute_b32 v102, v103, v100
	ds_bpermute_b32 v103, v103, v101
	v_cmp_gt_i32_e32 vcc, 32, v104
	s_waitcnt lgkmcnt(0)
	v_add_f64 v[102:103], v[100:101], v[102:103]
	v_cndmask_b32_e32 v101, v103, v101, vcc
	v_cndmask_b32_e32 v100, v102, v100, vcc
	v_add_f64 v[100:101], v[100:101], -v[98:99]
	v_add_f64 v[84:85], v[84:85], v[100:101]
	v_add_f64 v[68:69], v[84:85], -v[68:69]
	v_add_f64 v[84:85], v[86:87], v[100:101]
	v_add_f64 v[70:71], v[84:85], -v[70:71]
	ds_write2_b64 v106, v[68:69], v[70:71] offset1:8
	v_add_f64 v[68:69], v[88:89], v[100:101]
	v_add_f64 v[70:71], v[90:91], v[100:101]
	v_add_f64 v[68:69], v[68:69], -v[72:73]
	v_add_f64 v[70:71], v[70:71], -v[74:75]
	ds_write2_b64 v106, v[68:69], v[70:71] offset0:16 offset1:24
	v_add_f64 v[68:69], v[92:93], v[100:101]
	v_add_f64 v[70:71], v[94:95], v[100:101]
	v_add_f64 v[68:69], v[68:69], -v[76:77]
	v_add_f64 v[70:71], v[70:71], -v[78:79]
	ds_write2_b64 v106, v[68:69], v[70:71] offset0:32 offset1:40
	v_add_f64 v[68:69], v[96:97], v[100:101]
	v_add_f64 v[70:71], v[98:99], v[100:101]
	v_add_f64 v[68:69], v[68:69], -v[80:81]
	v_add_f64 v[70:71], v[70:71], -v[82:83]
	ds_write2_b64 v106, v[68:69], v[70:71] offset0:48 offset1:56
	s_waitcnt lgkmcnt(0)
	s_barrier
	ds_read_b128 v[68:71], v105
	ds_read_b128 v[72:75], v105 offset:16
	ds_read_b128 v[76:79], v105 offset:32
	ds_read_b128 v[80:83], v105 offset:48
	s_waitcnt lgkmcnt(3)
	v_add_f64 v[68:69], v[68:69], v[66:67]
	v_add_f64 v[64:65], v[68:69], v[64:65]
	v_add_f64 v[62:63], v[64:65], v[62:63]
	v_add_f64 v[60:61], v[62:63], v[60:61]
	v_mul_f64 v[66:67], v[68:69], s[2:3]
	v_mul_f64 v[68:69], v[64:65], s[2:3]
	v_mul_f64 v[64:65], v[62:63], s[2:3]
	v_mul_f64 v[60:61], v[60:61], s[2:3]
	v_lshlrev_b64 v[62:63], 2, v[42:43]
	v_cvt_f32_f64_e32 v66, v[66:67]
	v_cvt_f32_f64_e32 v67, v[68:69]
	v_cvt_f32_f64_e32 v68, v[64:65]
	v_cvt_f32_f64_e32 v69, v[60:61]
	v_lshl_add_u64 v[42:43], s[4:5], 0, v[62:63]
	global_store_dwordx4 v[42:43], v[66:69], off
	v_add_f64 v[42:43], v[70:71], v[58:59]
	s_or_b32 s4, s0, 1
	v_mul_f64 v[58:59], v[42:43], s[2:3]
	v_add_f64 v[42:43], v[42:43], v[56:57]
	s_ashr_i32 s5, s4, 31
	v_mul_f64 v[56:57], v[42:43], s[2:3]
	v_add_f64 v[42:43], v[42:43], v[54:55]
	s_lshl_b64 s[4:5], s[4:5], 13
	v_mul_f64 v[54:55], v[42:43], s[2:3]
	v_add_f64 v[42:43], v[42:43], v[52:53]
	s_add_u32 s4, s48, s4
	v_mul_f64 v[42:43], v[42:43], s[2:3]
	s_addc_u32 s5, s49, s5
	v_cvt_f32_f64_e32 v58, v[58:59]
	v_cvt_f32_f64_e32 v59, v[56:57]
	v_cvt_f32_f64_e32 v60, v[54:55]
	v_cvt_f32_f64_e32 v61, v[42:43]
	v_lshl_add_u64 v[42:43], s[4:5], 0, v[62:63]
	global_store_dwordx4 v[42:43], v[58:61], off
	s_waitcnt lgkmcnt(2)
	v_add_f64 v[42:43], v[72:73], v[50:51]
	s_or_b32 s4, s0, 2
	v_mul_f64 v[50:51], v[42:43], s[2:3]
	v_add_f64 v[42:43], v[42:43], v[48:49]
	s_ashr_i32 s5, s4, 31
	v_mul_f64 v[48:49], v[42:43], s[2:3]
	v_add_f64 v[42:43], v[42:43], v[46:47]
	s_lshl_b64 s[4:5], s[4:5], 13
	v_mul_f64 v[46:47], v[42:43], s[2:3]
	v_add_f64 v[42:43], v[42:43], v[44:45]
	s_add_u32 s4, s48, s4
	v_mul_f64 v[42:43], v[42:43], s[2:3]
	s_addc_u32 s5, s49, s5
	v_cvt_f32_f64_e32 v50, v[50:51]
	v_cvt_f32_f64_e32 v51, v[48:49]
	v_cvt_f32_f64_e32 v52, v[46:47]
	v_cvt_f32_f64_e32 v53, v[42:43]
	v_lshl_add_u64 v[42:43], s[4:5], 0, v[62:63]
	global_store_dwordx4 v[42:43], v[50:53], off
	v_add_f64 v[42:43], v[74:75], v[40:41]
	s_or_b32 s4, s0, 3
	v_add_f64 v[38:39], v[42:43], v[38:39]
	s_ashr_i32 s5, s4, 31
	v_add_f64 v[36:37], v[38:39], v[36:37]
	s_lshl_b64 s[4:5], s[4:5], 13
	v_add_f64 v[34:35], v[36:37], v[34:35]
	s_add_u32 s4, s48, s4
	v_mul_f64 v[40:41], v[42:43], s[2:3]
	v_mul_f64 v[42:43], v[38:39], s[2:3]
	v_mul_f64 v[38:39], v[36:37], s[2:3]
	v_mul_f64 v[34:35], v[34:35], s[2:3]
	s_addc_u32 s5, s49, s5
	v_cvt_f32_f64_e32 v40, v[40:41]
	v_cvt_f32_f64_e32 v41, v[42:43]
	v_cvt_f32_f64_e32 v42, v[38:39]
	v_cvt_f32_f64_e32 v43, v[34:35]
	v_lshl_add_u64 v[34:35], s[4:5], 0, v[62:63]
	global_store_dwordx4 v[34:35], v[40:43], off
	s_waitcnt lgkmcnt(1)
	v_add_f64 v[34:35], v[76:77], v[32:33]
	s_or_b32 s4, s0, 4
	v_add_f64 v[30:31], v[34:35], v[30:31]
	s_ashr_i32 s5, s4, 31
	v_add_f64 v[28:29], v[30:31], v[28:29]
	s_lshl_b64 s[4:5], s[4:5], 13
	v_add_f64 v[26:27], v[28:29], v[26:27]
	s_add_u32 s4, s48, s4
	v_mul_f64 v[32:33], v[34:35], s[2:3]
	v_mul_f64 v[34:35], v[30:31], s[2:3]
	v_mul_f64 v[30:31], v[28:29], s[2:3]
	v_mul_f64 v[26:27], v[26:27], s[2:3]
	s_addc_u32 s5, s49, s5
	v_cvt_f32_f64_e32 v32, v[32:33]
	v_cvt_f32_f64_e32 v33, v[34:35]
	v_cvt_f32_f64_e32 v34, v[30:31]
	v_cvt_f32_f64_e32 v35, v[26:27]
	v_lshl_add_u64 v[26:27], s[4:5], 0, v[62:63]
	global_store_dwordx4 v[26:27], v[32:35], off
	v_add_f64 v[26:27], v[78:79], v[24:25]
	s_or_b32 s4, s0, 5
	v_add_f64 v[22:23], v[26:27], v[22:23]
	s_ashr_i32 s5, s4, 31
	v_add_f64 v[20:21], v[22:23], v[20:21]
	s_lshl_b64 s[4:5], s[4:5], 13
	v_add_f64 v[18:19], v[20:21], v[18:19]
	s_add_u32 s4, s48, s4
	v_mul_f64 v[24:25], v[26:27], s[2:3]
	v_mul_f64 v[26:27], v[22:23], s[2:3]
	v_mul_f64 v[22:23], v[20:21], s[2:3]
	v_mul_f64 v[18:19], v[18:19], s[2:3]
	s_addc_u32 s5, s49, s5
	v_cvt_f32_f64_e32 v24, v[24:25]
	v_cvt_f32_f64_e32 v25, v[26:27]
	v_cvt_f32_f64_e32 v26, v[22:23]
	v_cvt_f32_f64_e32 v27, v[18:19]
	v_lshl_add_u64 v[18:19], s[4:5], 0, v[62:63]
	global_store_dwordx4 v[18:19], v[24:27], off
	s_waitcnt lgkmcnt(0)
	v_add_f64 v[18:19], v[80:81], v[16:17]
	s_or_b32 s4, s0, 6
	v_add_f64 v[14:15], v[18:19], v[14:15]
	s_ashr_i32 s5, s4, 31
	v_add_f64 v[12:13], v[14:15], v[12:13]
	s_lshl_b64 s[4:5], s[4:5], 13
	v_add_f64 v[10:11], v[12:13], v[10:11]
	s_add_u32 s4, s48, s4
	v_mul_f64 v[16:17], v[18:19], s[2:3]
	v_mul_f64 v[18:19], v[14:15], s[2:3]
	v_mul_f64 v[14:15], v[12:13], s[2:3]
	v_mul_f64 v[10:11], v[10:11], s[2:3]
	s_addc_u32 s5, s49, s5
	v_cvt_f32_f64_e32 v16, v[16:17]
	v_cvt_f32_f64_e32 v17, v[18:19]
	v_cvt_f32_f64_e32 v18, v[14:15]
	v_cvt_f32_f64_e32 v19, v[10:11]
	v_lshl_add_u64 v[10:11], s[4:5], 0, v[62:63]
	global_store_dwordx4 v[10:11], v[16:19], off
	v_add_f64 v[10:11], v[82:83], v[8:9]
	s_or_b32 s0, s0, 7
	v_add_f64 v[6:7], v[10:11], v[6:7]
	s_ashr_i32 s1, s0, 31
	v_add_f64 v[4:5], v[6:7], v[4:5]
	s_lshl_b64 s[0:1], s[0:1], 13
	v_add_f64 v[2:3], v[4:5], v[2:3]
	s_add_u32 s0, s48, s0
	v_mul_f64 v[8:9], v[10:11], s[2:3]
	v_mul_f64 v[10:11], v[6:7], s[2:3]
	v_mul_f64 v[6:7], v[4:5], s[2:3]
	v_mul_f64 v[2:3], v[2:3], s[2:3]
	s_addc_u32 s1, s49, s1
	v_cvt_f32_f64_e32 v8, v[8:9]
	v_cvt_f32_f64_e32 v9, v[10:11]
	v_cvt_f32_f64_e32 v10, v[6:7]
	v_cvt_f32_f64_e32 v11, v[2:3]
	v_lshl_add_u64 v[2:3], s[0:1], 0, v[62:63]
	global_store_dwordx4 v[2:3], v[8:11], off
	s_barrier

.LBB0_588:
	s_cmpk_eq_i32 s38, 0x400
	s_cselect_b64 s[4:5], -1, 0
	s_and_b64 s[4:5], s[4:5], s[14:15]
	s_andn2_b64 vcc, exec, s[4:5]
	s_cbranch_vccnz .LBB0_587
	s_and_b64 vcc, exec, s[12:13]
	s_cbranch_vccz .Lhook3_go
	s_barrier
.Lhook3_go:
	s_mov_b64 s[4:5], s[84:85]
	s_and_b32 s5, s5, 0xffff
	buffer_load_dwordx4 v[176:179], v174, s[4:7], s51 offen
	buffer_load_dwordx4 v[180:183], v174, s[4:7], s52 offen
	buffer_load_dwordx4 v[184:187], v174, s[4:7], 0 offen
	buffer_load_dwordx4 v[188:191], v174, s[4:7], s46 offen
	buffer_load_dwordx4 v[192:195], v174, s[4:7], s50 offen
	buffer_load_dwordx4 v[218:221], v174, s[4:7], s49 offen
	buffer_load_dwordx4 v[222:225], v174, s[4:7], s53 offen
	buffer_load_dwordx4 v[166:169], v174, s[4:7], s54 offen
	buffer_load_dwordx4 v[162:165], v174, s[4:7], s55 offen
	buffer_load_dwordx4 v[158:161], v174, s[4:7], s56 offen
	buffer_load_dwordx4 v[154:157], v174, s[4:7], s57 offen
	buffer_load_dwordx4 v[150:153], v174, s[4:7], s58 offen
	buffer_load_dwordx4 v[146:149], v174, s[4:7], s59 offen
	buffer_load_dwordx4 v[142:145], v174, s[4:7], s60 offen
	buffer_load_dwordx4 v[138:141], v174, s[4:7], s61 offen
	buffer_load_dwordx4 v[134:137], v174, s[4:7], s62 offen
	s_waitcnt vmcnt(0)
	v_lshlrev_b32_e32 v4, 16, v184
	v_and_b32_e32 v5, 0xffff0000, v184
	v_pk_mul_f32 v[130:131], v[130:131], v[4:5]
	v_lshlrev_b32_e32 v4, 16, v186
	v_and_b32_e32 v5, 0xffff0000, v186
	v_pk_mul_f32 v[126:127], v[126:127], v[4:5]
	v_lshlrev_b32_e32 v4, 16, v176
	v_and_b32_e32 v5, 0xffff0000, v176
	v_pk_mul_f32 v[122:123], v[122:123], v[4:5]
	v_lshlrev_b32_e32 v4, 16, v178
	v_and_b32_e32 v5, 0xffff0000, v178
	v_pk_mul_f32 v[118:119], v[118:119], v[4:5]
	v_lshlrev_b32_e32 v4, 16, v192
	v_and_b32_e32 v5, 0xffff0000, v192
	v_pk_mul_f32 v[114:115], v[114:115], v[4:5]
	v_lshlrev_b32_e32 v4, 16, v194
	v_and_b32_e32 v5, 0xffff0000, v194
	v_pk_mul_f32 v[110:111], v[110:111], v[4:5]
	v_lshlrev_b32_e32 v4, 16, v180
	v_and_b32_e32 v5, 0xffff0000, v180
	v_pk_mul_f32 v[106:107], v[106:107], v[4:5]
	v_lshlrev_b32_e32 v4, 16, v182
	v_and_b32_e32 v5, 0xffff0000, v182
	v_pk_mul_f32 v[102:103], v[102:103], v[4:5]
	v_lshlrev_b32_e32 v4, 16, v188
	v_and_b32_e32 v5, 0xffff0000, v188
	v_pk_mul_f32 v[98:99], v[98:99], v[4:5]
	v_lshlrev_b32_e32 v4, 16, v190
	v_and_b32_e32 v5, 0xffff0000, v190
	v_pk_mul_f32 v[94:95], v[94:95], v[4:5]
	v_lshlrev_b32_e32 v4, 16, v222
	v_and_b32_e32 v5, 0xffff0000, v222
	v_pk_mul_f32 v[90:91], v[90:91], v[4:5]
	v_lshlrev_b32_e32 v4, 16, v224
	v_and_b32_e32 v5, 0xffff0000, v224
	v_pk_mul_f32 v[86:87], v[86:87], v[4:5]
	v_lshlrev_b32_e32 v4, 16, v218
	v_and_b32_e32 v5, 0xffff0000, v218
	v_pk_mul_f32 v[82:83], v[82:83], v[4:5]
	v_lshlrev_b32_e32 v4, 16, v220
	v_and_b32_e32 v5, 0xffff0000, v220
	v_pk_mul_f32 v[78:79], v[78:79], v[4:5]
	v_lshlrev_b32_e32 v4, 16, v166
	v_and_b32_e32 v5, 0xffff0000, v166
	v_pk_mul_f32 v[74:75], v[74:75], v[4:5]
	v_lshlrev_b32_e32 v4, 16, v168
	v_and_b32_e32 v5, 0xffff0000, v168
	v_pk_mul_f32 v[70:71], v[70:71], v[4:5]
	v_lshlrev_b32_e32 v4, 16, v162
	v_and_b32_e32 v5, 0xffff0000, v162
	v_pk_mul_f32 v[66:67], v[66:67], v[4:5]
	v_lshlrev_b32_e32 v4, 16, v164
	v_and_b32_e32 v5, 0xffff0000, v164
	v_pk_mul_f32 v[62:63], v[62:63], v[4:5]
	v_lshlrev_b32_e32 v4, 16, v158
	v_and_b32_e32 v5, 0xffff0000, v158
	v_pk_mul_f32 v[58:59], v[58:59], v[4:5]
	v_lshlrev_b32_e32 v4, 16, v160
	v_and_b32_e32 v5, 0xffff0000, v160
	v_lshlrev_b32_e32 v176, 16, v177
	v_and_b32_e32 v177, 0xffff0000, v177
	v_pk_mul_f32 v[54:55], v[54:55], v[4:5]
	v_lshlrev_b32_e32 v4, 16, v154
	v_and_b32_e32 v5, 0xffff0000, v154
	v_pk_mul_f32 v[124:125], v[124:125], v[176:177]
	v_lshlrev_b32_e32 v176, 16, v179
	v_and_b32_e32 v177, 0xffff0000, v179
	v_pk_mul_f32 v[50:51], v[50:51], v[4:5]
	v_lshlrev_b32_e32 v4, 16, v156
	v_and_b32_e32 v5, 0xffff0000, v156
	v_pk_mul_f32 v[120:121], v[120:121], v[176:177]
	v_lshlrev_b32_e32 v176, 16, v193
	v_and_b32_e32 v177, 0xffff0000, v193
	v_pk_mul_f32 v[46:47], v[46:47], v[4:5]
	v_lshlrev_b32_e32 v4, 16, v150
	v_and_b32_e32 v5, 0xffff0000, v150
	v_pk_mul_f32 v[116:117], v[116:117], v[176:177]
	v_lshlrev_b32_e32 v176, 16, v195
	v_and_b32_e32 v177, 0xffff0000, v195
	v_pk_mul_f32 v[42:43], v[42:43], v[4:5]
	v_lshlrev_b32_e32 v4, 16, v152
	v_and_b32_e32 v5, 0xffff0000, v152
	v_pk_mul_f32 v[112:113], v[112:113], v[176:177]
	v_lshlrev_b32_e32 v176, 16, v181
	v_and_b32_e32 v177, 0xffff0000, v181
	v_pk_mul_f32 v[38:39], v[38:39], v[4:5]
	v_lshlrev_b32_e32 v4, 16, v146
	v_and_b32_e32 v5, 0xffff0000, v146
	v_pk_mul_f32 v[108:109], v[108:109], v[176:177]
	v_lshlrev_b32_e32 v176, 16, v183
	v_and_b32_e32 v177, 0xffff0000, v183
	v_pk_mul_f32 v[34:35], v[34:35], v[4:5]
	v_lshlrev_b32_e32 v4, 16, v148
	v_and_b32_e32 v5, 0xffff0000, v148
	v_pk_mul_f32 v[104:105], v[104:105], v[176:177]
	v_lshlrev_b32_e32 v176, 16, v189
	v_and_b32_e32 v177, 0xffff0000, v189
	v_pk_mul_f32 v[30:31], v[30:31], v[4:5]
	v_lshlrev_b32_e32 v4, 16, v142
	v_and_b32_e32 v5, 0xffff0000, v142
	v_pk_mul_f32 v[100:101], v[100:101], v[176:177]
	v_lshlrev_b32_e32 v176, 16, v191
	v_and_b32_e32 v177, 0xffff0000, v191
	v_pk_mul_f32 v[26:27], v[26:27], v[4:5]
	v_lshlrev_b32_e32 v4, 16, v144
	v_and_b32_e32 v5, 0xffff0000, v144
	v_pk_mul_f32 v[96:97], v[96:97], v[176:177]
	v_lshlrev_b32_e32 v176, 16, v223
	v_and_b32_e32 v177, 0xffff0000, v223
	v_pk_mul_f32 v[22:23], v[22:23], v[4:5]
	v_lshlrev_b32_e32 v4, 16, v138
	v_and_b32_e32 v5, 0xffff0000, v138
	v_pk_mul_f32 v[92:93], v[92:93], v[176:177]
	v_lshlrev_b32_e32 v176, 16, v225
	v_and_b32_e32 v177, 0xffff0000, v225
	v_pk_mul_f32 v[18:19], v[18:19], v[4:5]
	v_lshlrev_b32_e32 v4, 16, v140
	v_and_b32_e32 v5, 0xffff0000, v140
	v_lshlrev_b32_e32 v184, 16, v185
	v_and_b32_e32 v185, 0xffff0000, v185
	v_pk_mul_f32 v[88:89], v[88:89], v[176:177]
	v_lshlrev_b32_e32 v176, 16, v219
	v_and_b32_e32 v177, 0xffff0000, v219
	v_lshlrev_b32_e32 v166, 16, v167
	v_and_b32_e32 v167, 0xffff0000, v167
	v_lshlrev_b32_e32 v162, 16, v163
	v_and_b32_e32 v163, 0xffff0000, v163
	v_lshlrev_b32_e32 v158, 16, v159
	v_and_b32_e32 v159, 0xffff0000, v159
	v_lshlrev_b32_e32 v154, 16, v155
	v_and_b32_e32 v155, 0xffff0000, v155
	v_lshlrev_b32_e32 v150, 16, v151
	v_and_b32_e32 v151, 0xffff0000, v151
	v_lshlrev_b32_e32 v146, 16, v147
	v_and_b32_e32 v147, 0xffff0000, v147
	v_lshlrev_b32_e32 v142, 16, v143
	v_and_b32_e32 v143, 0xffff0000, v143
	v_lshlrev_b32_e32 v138, 16, v139
	v_and_b32_e32 v139, 0xffff0000, v139
	v_pk_mul_f32 v[14:15], v[14:15], v[4:5]
	v_lshlrev_b32_e32 v4, 16, v134
	v_and_b32_e32 v5, 0xffff0000, v134
	v_lshlrev_b32_e32 v134, 16, v135
	v_and_b32_e32 v135, 0xffff0000, v135
	v_pk_mul_f32 v[132:133], v[132:133], v[184:185]
	v_lshlrev_b32_e32 v184, 16, v187
	v_and_b32_e32 v185, 0xffff0000, v187
	v_pk_mul_f32 v[84:85], v[84:85], v[176:177]
	v_lshlrev_b32_e32 v176, 16, v221
	v_and_b32_e32 v177, 0xffff0000, v221
	v_pk_mul_f32 v[76:77], v[76:77], v[166:167]
	v_lshlrev_b32_e32 v166, 16, v169
	v_and_b32_e32 v167, 0xffff0000, v169
	v_pk_mul_f32 v[68:69], v[68:69], v[162:163]
	v_lshlrev_b32_e32 v162, 16, v165
	v_and_b32_e32 v163, 0xffff0000, v165
	v_pk_mul_f32 v[60:61], v[60:61], v[158:159]
	v_lshlrev_b32_e32 v158, 16, v161
	v_and_b32_e32 v159, 0xffff0000, v161
	v_pk_mul_f32 v[52:53], v[52:53], v[154:155]
	v_lshlrev_b32_e32 v154, 16, v157
	v_and_b32_e32 v155, 0xffff0000, v157
	v_pk_mul_f32 v[44:45], v[44:45], v[150:151]
	v_lshlrev_b32_e32 v150, 16, v153
	v_and_b32_e32 v151, 0xffff0000, v153
	v_pk_mul_f32 v[36:37], v[36:37], v[146:147]
	v_lshlrev_b32_e32 v146, 16, v149
	v_and_b32_e32 v147, 0xffff0000, v149
	v_pk_mul_f32 v[28:29], v[28:29], v[142:143]
	v_lshlrev_b32_e32 v142, 16, v145
	v_and_b32_e32 v143, 0xffff0000, v145
	v_pk_mul_f32 v[20:21], v[20:21], v[138:139]
	v_lshlrev_b32_e32 v138, 16, v141
	v_and_b32_e32 v139, 0xffff0000, v141
	v_pk_mul_f32 v[12:13], v[12:13], v[134:135]
	v_pk_mul_f32 v[10:11], v[10:11], v[4:5]
	v_lshlrev_b32_e32 v4, 16, v136
	v_and_b32_e32 v5, 0xffff0000, v136
	v_lshlrev_b32_e32 v134, 16, v137
	v_and_b32_e32 v135, 0xffff0000, v137
	v_pk_mul_f32 v[128:129], v[128:129], v[184:185]
	v_pk_mul_f32 v[80:81], v[80:81], v[176:177]
	v_pk_mul_f32 v[72:73], v[72:73], v[166:167]
	v_pk_mul_f32 v[64:65], v[64:65], v[162:163]
	v_pk_mul_f32 v[56:57], v[56:57], v[158:159]
	v_pk_mul_f32 v[48:49], v[48:49], v[154:155]
	v_pk_mul_f32 v[40:41], v[40:41], v[150:151]
	v_pk_mul_f32 v[32:33], v[32:33], v[146:147]
	v_pk_mul_f32 v[24:25], v[24:25], v[142:143]
	v_pk_mul_f32 v[16:17], v[16:17], v[138:139]
	v_pk_mul_f32 v[8:9], v[8:9], v[134:135]
	v_pk_mul_f32 v[6:7], v[6:7], v[4:5]
	s_andn2_b64 vcc, exec, s[8:9]
	s_cbranch_vccnz .LBB0_587
	s_barrier
	s_branch .LBB0_587
